# MLA loop: one static s_setprio 1 for waves 4-7 for the whole attention loop (reset at phase end)
# baseline (speedup 1.0000x reference)
; #define MLA_DMA(t, slot) do { _Pragma("unroll") for (int i_ = 0; i_ < 4; ++i_) { const bf16_t* src_ = (pisk[i_] ? kbase : vbase) + poff[i_] + (size_t)(t) * pstep[i_]; \
;         __builtin_amdgcn_global_load_lds((const unsigned*)src_, (LAS unsigned*)(lds + (slot) * SLOT + (w + 8 * i_) * 1024), 16, 0, 0); } } while (0)
; DI void mla_attn_phase(LAS unsigned char* lds, const bf16_t* Qg, const bf16_t* Kg, const bf16_t* Vtg, bf16_t* MIX) {
;     ...
;             const int qb = half ? pi : 63 - pi, q0 = qb * 256 + 32 * w, NT = 4 * (qb + 1);
;     ...
;             const bf16_t* qp = Qg + ((size_t)bh * SEQ + q0 + r32) * 96 + 8 * hf;
;             bf16x8 qf[6];
; #pragma unroll
;             for (int ks = 0; ks < 6; ++ks) qf[ks] = *(const bf16x8*)(qp + 16 * ks);
;             asm volatile("" ::: "memory");
;             MLA_DMA(0, 0); MLA_DMA(1, 1);
;             f32x16 o[4];
; #pragma unroll
;             for (int mt = 0; mt < 4; ++mt)
; #pragma unroll
;                 for (int i = 0; i < 16; ++i) o[mt][i] = 0.f;
;             float m_run = -1e30f, l_run = 0.f;
;     ...
;             asm volatile("s_waitcnt vmcnt(4)" ::: "memory");
;             __builtin_amdgcn_s_barrier(); asm volatile("" ::: "memory");
;             int sl = 0;
.LBB0_357:
	s_and_b64 s[26:27], s[24:25], exec
	s_cselect_b32 s8, s37, s36
	s_lshl_b32 s26, s8, 8
	s_add_i32 s26, s26, s34
	s_ashr_i32 s27, s26, 31
	v_lshl_add_u64 v[0:1], v[180:181], 0, s[26:27]
	s_movk_i32 s30, 0xc0
	s_waitcnt lgkmcnt(0)
	v_mad_u64_u32 v[4:5], s[28:29], v0, s30, v[168:169]
	v_mad_i32_i24 v5, v1, s30, v5
	s_mov_b32 m0, s35
	global_load_dwordx4 v[112:115], v[4:5], off
	global_load_dwordx4 v[116:119], v[4:5], off offset:32
	global_load_dwordx4 v[120:123], v[4:5], off offset:64
	global_load_dwordx4 v[124:127], v[4:5], off offset:96
	global_load_dwordx4 v[128:131], v[4:5], off offset:128
	global_load_dwordx4 v[132:135], v[4:5], off offset:160
	global_load_lds_dwordx4 v[184:185], off
	s_add_i32 m0, s35, 0x2000
	s_nop 0
	global_load_lds_dwordx4 v[186:187], off
	s_add_i32 m0, s35, 0x4000
	s_nop 0
	global_load_lds_dwordx4 v[188:189], off
	s_add_i32 m0, s35, 0x6000
	s_nop 0
	global_load_lds_dwordx4 v[190:191], off
	s_add_i32 m0, s35, 0x8000
	s_nop 0
	global_load_lds_dwordx4 v[192:193], off
	s_add_i32 m0, s35, 0xa000
	s_nop 0
	global_load_lds_dwordx4 v[194:195], off
	s_add_i32 m0, s35, 0xc000
	s_nop 0
	global_load_lds_dwordx4 v[196:197], off
	s_add_i32 m0, s35, 0xe000
	s_cmp_lt_i32 s8, 0
	global_load_lds_dwordx4 v[198:199], off
	s_waitcnt vmcnt(4)
	s_barrier
	s_cbranch_scc1 .LBB0_355
	s_waitcnt lgkmcnt(0)
	v_mov_b32_e32 v14, v2
	v_mov_b32_e32 v15, v2
	s_lshl_b32 s8, s8, 2
	v_mov_b32_e32 v0, v2
	v_mov_b32_e32 v1, v2
	v_mov_b32_e32 v3, v2
	v_mov_b32_e32 v4, v2
	v_mov_b32_e32 v5, v2
	v_mov_b32_e32 v6, v2
	v_mov_b32_e32 v7, v2
	v_mov_b32_e32 v8, v2
	v_mov_b32_e32 v9, v2
	v_mov_b32_e32 v10, v2
	v_mov_b32_e32 v11, v2
	v_mov_b32_e32 v12, v2
	v_mov_b32_e32 v13, v2
	v_mov_b64_e32 v[30:31], v[14:15]
	v_mov_b64_e32 v[46:47], v[14:15]
	v_mov_b64_e32 v[62:63], v[14:15]
	v_mov_b64_e32 v[78:79], v[14:15]
	s_add_i32 s38, s8, 4
	s_or_b32 s39, s26, 31
	v_or_b32_e32 v167, s26, v164
	s_mov_b32 s40, 0
	v_mov_b32_e32 v234, 0xf149f2ca
	v_mov_b32_e32 v233, 0
	v_mov_b64_e32 v[210:211], v[208:209]
	v_mov_b64_e32 v[212:213], v[206:207]
	v_mov_b64_e32 v[214:215], v[204:205]
	v_mov_b64_e32 v[216:217], v[202:203]
	v_mov_b64_e32 v[28:29], v[12:13]
	v_mov_b64_e32 v[26:27], v[10:11]
	v_mov_b64_e32 v[24:25], v[8:9]
	v_mov_b64_e32 v[22:23], v[6:7]
	v_mov_b64_e32 v[20:21], v[4:5]
	v_mov_b64_e32 v[18:19], v[2:3]
	v_mov_b64_e32 v[16:17], v[0:1]
	v_mov_b64_e32 v[44:45], v[12:13]
	v_mov_b64_e32 v[42:43], v[10:11]
	v_mov_b64_e32 v[40:41], v[8:9]
	v_mov_b64_e32 v[38:39], v[6:7]
	v_mov_b64_e32 v[36:37], v[4:5]
	v_mov_b64_e32 v[34:35], v[2:3]
	v_mov_b64_e32 v[32:33], v[0:1]
	v_mov_b64_e32 v[60:61], v[12:13]
	v_mov_b64_e32 v[58:59], v[10:11]
	v_mov_b64_e32 v[56:57], v[8:9]
	v_mov_b64_e32 v[54:55], v[6:7]
	v_mov_b64_e32 v[52:53], v[4:5]
	v_mov_b64_e32 v[50:51], v[2:3]
	v_mov_b64_e32 v[48:49], v[0:1]
	v_mov_b64_e32 v[76:77], v[12:13]
	v_mov_b64_e32 v[74:75], v[10:11]
	v_mov_b64_e32 v[72:73], v[8:9]
	v_mov_b64_e32 v[70:71], v[6:7]
	v_mov_b64_e32 v[68:69], v[4:5]
	v_mov_b64_e32 v[66:67], v[2:3]
	v_mov_b64_e32 v[64:65], v[0:1]
	s_mov_b32 s41, 0
	s_mov_b32 s42, 0
	s_waitcnt vmcnt(0)
	s_cmp_lt_u32 s34, 0x80
	s_cbranch_scc1 .Lmla_pro_done
	s_add_i32 s31, s35, 0x10000
	s_mov_b32 m0, s31
	s_nop 0
	global_load_lds_dwordx4 v[210:211], off
	s_add_i32 m0, s31, 0x2000
	s_nop 0
	global_load_lds_dwordx4 v[212:213], off
	s_add_i32 m0, s31, 0x4000
	s_nop 0
	global_load_lds_dwordx4 v[214:215], off
	s_add_i32 m0, s31, 0x6000
	s_nop 0
	global_load_lds_dwordx4 v[216:217], off
	v_lshl_add_u64 v[216:217], v[216:217], 0, s[18:19]
	v_lshl_add_u64 v[214:215], v[214:215], 0, s[20:21]
	v_lshl_add_u64 v[212:213], v[212:213], 0, s[2:3]
	v_lshl_add_u64 v[210:211], v[210:211], 0, s[22:23]
	s_setprio 1
	s_barrier
